# fast path for the two weight-transpose loops hipcc serialised (prologue FFN-in(0,0), row_ffn<1,0> KV): 32 nt loads in flight per wave instead of ~1; same arithmetic
# speedup vs baseline: 1.0098x; 1.0098x over previous
.LBB0_15:
	s_and_b64 vcc, exec, s[4:5]
	s_cbranch_vccz .LBB0_10
	s_mul_hi_i32 s10, s27, 0x2e8ba2e9
	s_lshr_b32 s14, s10, 31
	s_ashr_i32 s10, s10, 5
	s_load_dwordx2 s[4:5], s[0:1], 0x18
	s_add_i32 s14, s10, s14
	s_mul_i32 s10, s14, 0xb0
	s_sub_i32 s10, s27, s10
	s_lshl_b32 s16, s10, 5
	s_ashr_i32 s17, s16, 31
	s_lshl_b32 s14, s14, 6
	s_waitcnt lgkmcnt(0)
	v_lshl_add_u64 v[32:33], s[4:5], 0, v[10:11]
	s_lshl_b64 s[4:5], s[16:17], 2
	v_or_b32_e32 v4, s14, v40
	v_mov_b64_e32 v[48:49], s[4:5]
	v_mad_i64_i32 v[12:13], s[4:5], v4, s26, v[48:49]
	v_or_b32_e32 v4, s14, v41
	v_mad_i64_i32 v[16:17], s[4:5], v4, s26, v[48:49]
	v_or_b32_e32 v4, s14, v42
	v_mad_i64_i32 v[18:19], s[4:5], v4, s26, v[48:49]
	v_or_b32_e32 v4, s14, v43
	s_ashr_i32 s15, s14, 31
	v_mad_i64_i32 v[20:21], s[4:5], v4, s26, v[48:49]
	v_or_b32_e32 v4, s14, v44
	v_mov_b32_e32 v31, s15
	v_or_b32_e32 v30, s14, v2
	v_mad_i64_i32 v[22:23], s[4:5], v4, s26, v[48:49]
	v_or_b32_e32 v4, s14, v45
	v_lshlrev_b64 v[14:15], 2, v[30:31]
	v_mad_i64_i32 v[24:25], s[4:5], v4, s26, v[48:49]
	v_or_b32_e32 v4, s14, v46
	v_ashrrev_i32_e32 v31, 31, v30
	v_mad_i64_i32 v[26:27], s[4:5], v4, s26, v[48:49]
	v_lshlrev_b64 v[28:29], 2, v[30:31]
	v_mad_i64_i32 v[30:31], s[4:5], v30, s26, v[48:49]
	v_lshl_add_u64 v[12:13], v[32:33], 0, v[12:13]
	v_lshl_add_u64 v[16:17], v[32:33], 0, v[16:17]
	v_lshl_add_u64 v[18:19], v[32:33], 0, v[18:19]
	v_lshl_add_u64 v[20:21], v[32:33], 0, v[20:21]
	v_lshl_add_u64 v[22:23], v[32:33], 0, v[22:23]
	v_lshl_add_u64 v[24:25], v[32:33], 0, v[24:25]
	v_lshl_add_u64 v[26:27], v[32:33], 0, v[26:27]
	v_lshl_add_u64 v[30:31], v[32:33], 0, v[30:31]
	s_mov_b64 s[18:19], 0
	s_mov_b64 s[20:21], s[6:7]
	v_mov_b32_e32 v4, v39
	s_andn2_b64 vcc, exec, s[12:13]
	s_cbranch_vccnz .LBB0_18
	v_mov_b32_e32 v174, v30
	v_mov_b32_e32 v175, v31
	v_lshl_add_u64 v[176:177], s[6:7], 0, v[14:15]
	v_mov_b32_e32 v178, v39
	s_mov_b32 s50, 0xb000
	s_mov_b32 s51, 0
	global_load_dword v180, v[174:175], off nt
	v_lshl_add_u64 v[174:175], v[174:175], 0, s[50:51]
	global_load_dword v181, v[174:175], off nt
	v_lshl_add_u64 v[174:175], v[174:175], 0, s[50:51]
	global_load_dword v182, v[174:175], off nt
	v_lshl_add_u64 v[174:175], v[174:175], 0, s[50:51]
	global_load_dword v183, v[174:175], off nt
	v_lshl_add_u64 v[174:175], v[174:175], 0, s[50:51]
	global_load_dword v184, v[174:175], off nt
	v_lshl_add_u64 v[174:175], v[174:175], 0, s[50:51]
	global_load_dword v185, v[174:175], off nt
	v_lshl_add_u64 v[174:175], v[174:175], 0, s[50:51]
	global_load_dword v186, v[174:175], off nt
	v_lshl_add_u64 v[174:175], v[174:175], 0, s[50:51]
	global_load_dword v187, v[174:175], off nt
	v_lshl_add_u64 v[174:175], v[174:175], 0, s[50:51]
	global_load_dword v188, v[174:175], off nt
	v_lshl_add_u64 v[174:175], v[174:175], 0, s[50:51]
	global_load_dword v189, v[174:175], off nt
	v_lshl_add_u64 v[174:175], v[174:175], 0, s[50:51]
	global_load_dword v190, v[174:175], off nt
	v_lshl_add_u64 v[174:175], v[174:175], 0, s[50:51]
	global_load_dword v191, v[174:175], off nt
	v_lshl_add_u64 v[174:175], v[174:175], 0, s[50:51]
	global_load_dword v192, v[174:175], off nt
	v_lshl_add_u64 v[174:175], v[174:175], 0, s[50:51]
	global_load_dword v193, v[174:175], off nt
	v_lshl_add_u64 v[174:175], v[174:175], 0, s[50:51]
	global_load_dword v194, v[174:175], off nt
	v_lshl_add_u64 v[174:175], v[174:175], 0, s[50:51]
	global_load_dword v195, v[174:175], off nt
	v_lshl_add_u64 v[174:175], v[174:175], 0, s[50:51]
	global_load_dword v196, v[174:175], off nt
	v_lshl_add_u64 v[174:175], v[174:175], 0, s[50:51]
	global_load_dword v197, v[174:175], off nt
	v_lshl_add_u64 v[174:175], v[174:175], 0, s[50:51]
	global_load_dword v198, v[174:175], off nt
	v_lshl_add_u64 v[174:175], v[174:175], 0, s[50:51]
	global_load_dword v199, v[174:175], off nt
	v_lshl_add_u64 v[174:175], v[174:175], 0, s[50:51]
	global_load_dword v200, v[174:175], off nt
	v_lshl_add_u64 v[174:175], v[174:175], 0, s[50:51]
	global_load_dword v201, v[174:175], off nt
	v_lshl_add_u64 v[174:175], v[174:175], 0, s[50:51]
	global_load_dword v202, v[174:175], off nt
	v_lshl_add_u64 v[174:175], v[174:175], 0, s[50:51]
	global_load_dword v203, v[174:175], off nt
	v_lshl_add_u64 v[174:175], v[174:175], 0, s[50:51]
	global_load_dword v204, v[174:175], off nt
	v_lshl_add_u64 v[174:175], v[174:175], 0, s[50:51]
	global_load_dword v205, v[174:175], off nt
	v_lshl_add_u64 v[174:175], v[174:175], 0, s[50:51]
	global_load_dword v206, v[174:175], off nt
	v_lshl_add_u64 v[174:175], v[174:175], 0, s[50:51]
	global_load_dword v207, v[174:175], off nt
	v_lshl_add_u64 v[174:175], v[174:175], 0, s[50:51]
	global_load_dword v208, v[174:175], off nt
	v_lshl_add_u64 v[174:175], v[174:175], 0, s[50:51]
	global_load_dword v209, v[174:175], off nt
	v_lshl_add_u64 v[174:175], v[174:175], 0, s[50:51]
	global_load_dword v210, v[174:175], off nt
	v_lshl_add_u64 v[174:175], v[174:175], 0, s[50:51]
	global_load_dword v211, v[174:175], off nt
	global_load_dword v212, v[176:177], off
	global_load_dword v213, v[176:177], off offset:8
	global_load_dword v214, v[176:177], off offset:16
	global_load_dword v215, v[176:177], off offset:24
	global_load_dword v216, v[176:177], off offset:32
	global_load_dword v217, v[176:177], off offset:40
	global_load_dword v218, v[176:177], off offset:48
	global_load_dword v219, v[176:177], off offset:56
	global_load_dword v220, v[176:177], off offset:64
	global_load_dword v221, v[176:177], off offset:72
	global_load_dword v222, v[176:177], off offset:80
	global_load_dword v223, v[176:177], off offset:88
	global_load_dword v224, v[176:177], off offset:96
	global_load_dword v225, v[176:177], off offset:104
	global_load_dword v226, v[176:177], off offset:112
	global_load_dword v227, v[176:177], off offset:120
	s_waitcnt vmcnt(15)
	v_mul_f32_e32 v180, v180, v212
	ds_write_b32 v178, v180
	s_waitcnt vmcnt(14)
	v_mul_f32_e32 v181, v181, v213
	ds_write_b32 v178, v181 offset:264
	s_waitcnt vmcnt(13)
	v_mul_f32_e32 v182, v182, v214
	ds_write_b32 v178, v182 offset:528
	s_waitcnt vmcnt(12)
	v_mul_f32_e32 v183, v183, v215
	ds_write_b32 v178, v183 offset:792
	s_waitcnt vmcnt(11)
	v_mul_f32_e32 v184, v184, v216
	ds_write_b32 v178, v184 offset:1056
	s_waitcnt vmcnt(10)
	v_mul_f32_e32 v185, v185, v217
	ds_write_b32 v178, v185 offset:1320
	s_waitcnt vmcnt(9)
	v_mul_f32_e32 v186, v186, v218
	ds_write_b32 v178, v186 offset:1584
	s_waitcnt vmcnt(8)
	v_mul_f32_e32 v187, v187, v219
	ds_write_b32 v178, v187 offset:1848
	s_waitcnt vmcnt(7)
	v_mul_f32_e32 v188, v188, v220
	ds_write_b32 v178, v188 offset:2112
	s_waitcnt vmcnt(6)
	v_mul_f32_e32 v189, v189, v221
	ds_write_b32 v178, v189 offset:2376
	s_waitcnt vmcnt(5)
	v_mul_f32_e32 v190, v190, v222
	ds_write_b32 v178, v190 offset:2640
	s_waitcnt vmcnt(4)
	v_mul_f32_e32 v191, v191, v223
	ds_write_b32 v178, v191 offset:2904
	s_waitcnt vmcnt(3)
	v_mul_f32_e32 v192, v192, v224
	ds_write_b32 v178, v192 offset:3168
	s_waitcnt vmcnt(2)
	v_mul_f32_e32 v193, v193, v225
	ds_write_b32 v178, v193 offset:3432
	s_waitcnt vmcnt(1)
	v_mul_f32_e32 v194, v194, v226
	ds_write_b32 v178, v194 offset:3696
	s_waitcnt vmcnt(0)
	v_mul_f32_e32 v195, v195, v227
	ds_write_b32 v178, v195 offset:3960
	global_load_dword v212, v[176:177], off offset:128
	global_load_dword v213, v[176:177], off offset:136
	global_load_dword v214, v[176:177], off offset:144
	global_load_dword v215, v[176:177], off offset:152
	global_load_dword v216, v[176:177], off offset:160
	global_load_dword v217, v[176:177], off offset:168
	global_load_dword v218, v[176:177], off offset:176
	global_load_dword v219, v[176:177], off offset:184
	global_load_dword v220, v[176:177], off offset:192
	global_load_dword v221, v[176:177], off offset:200
	global_load_dword v222, v[176:177], off offset:208
	global_load_dword v223, v[176:177], off offset:216
	global_load_dword v224, v[176:177], off offset:224
	global_load_dword v225, v[176:177], off offset:232
	global_load_dword v226, v[176:177], off offset:240
	global_load_dword v227, v[176:177], off offset:248
	s_waitcnt vmcnt(15)
	v_mul_f32_e32 v196, v196, v212
	ds_write_b32 v178, v196 offset:4224
	s_waitcnt vmcnt(14)
	v_mul_f32_e32 v197, v197, v213
	ds_write_b32 v178, v197 offset:4488
	s_waitcnt vmcnt(13)
	v_mul_f32_e32 v198, v198, v214
	ds_write_b32 v178, v198 offset:4752
	s_waitcnt vmcnt(12)
	v_mul_f32_e32 v199, v199, v215
	ds_write_b32 v178, v199 offset:5016
	s_waitcnt vmcnt(11)
	v_mul_f32_e32 v200, v200, v216
	ds_write_b32 v178, v200 offset:5280
	s_waitcnt vmcnt(10)
	v_mul_f32_e32 v201, v201, v217
	ds_write_b32 v178, v201 offset:5544
	s_waitcnt vmcnt(9)
	v_mul_f32_e32 v202, v202, v218
	ds_write_b32 v178, v202 offset:5808
	s_waitcnt vmcnt(8)
	v_mul_f32_e32 v203, v203, v219
	ds_write_b32 v178, v203 offset:6072
	s_waitcnt vmcnt(7)
	v_mul_f32_e32 v204, v204, v220
	ds_write_b32 v178, v204 offset:6336
	s_waitcnt vmcnt(6)
	v_mul_f32_e32 v205, v205, v221
	ds_write_b32 v178, v205 offset:6600
	s_waitcnt vmcnt(5)
	v_mul_f32_e32 v206, v206, v222
	ds_write_b32 v178, v206 offset:6864
	s_waitcnt vmcnt(4)
	v_mul_f32_e32 v207, v207, v223
	ds_write_b32 v178, v207 offset:7128
	s_waitcnt vmcnt(3)
	v_mul_f32_e32 v208, v208, v224
	ds_write_b32 v178, v208 offset:7392
	s_waitcnt vmcnt(2)
	v_mul_f32_e32 v209, v209, v225
	ds_write_b32 v178, v209 offset:7656
	s_waitcnt vmcnt(1)
	v_mul_f32_e32 v210, v210, v226
	ds_write_b32 v178, v210 offset:7920
	s_waitcnt vmcnt(0)
	v_mul_f32_e32 v211, v211, v227
	ds_write_b32 v178, v211 offset:8184
	s_branch .LBB0_34

.LBB0_1428:
	s_cmpk_gt_i32 s33, 0x1ff
	s_mov_b64 s[8:9], -1
	s_cbranch_scc0 .LBB0_1448
	s_bfe_u32 s9, s20, 0xa0006
	s_lshl_b32 s8, s18, 2
	s_lshl_b32 s10, s9, 6
	s_and_b32 s8, s8, 0x1f80
	v_or_b32_e32 v0, s10, v39
	v_lshl_or_b32 v14, v0, 13, s8
	v_or_b32_e32 v0, s10, v40
	s_load_dwordx4 s[12:15], s[0:1], 0x58
	v_lshl_or_b32 v16, v0, 13, s8
	v_or_b32_e32 v0, s10, v41
	v_lshl_or_b32 v18, v0, 13, s8
	v_or_b32_e32 v0, s10, v42
	v_lshl_or_b32 v20, v0, 13, s8
	v_or_b32_e32 v0, s10, v43
	v_lshl_or_b32 v22, v0, 13, s8
	v_or_b32_e32 v0, s10, v44
	v_lshl_or_b32 v24, v0, 13, s8
	v_or_b32_e32 v0, s10, v45
	v_or_b32_e32 v11, s10, v32
	s_waitcnt lgkmcnt(0)
	s_cmp_lg_u64 s[12:13], 0
	v_lshl_or_b32 v12, s9, 8, v8
	v_lshl_or_b32 v26, v0, 13, s8
	v_lshl_or_b32 v28, v11, 13, s8
	s_cselect_b64 s[8:9], -1, 0
	v_mov_b32_e32 v15, v1
	v_mov_b32_e32 v17, v1
	v_mov_b32_e32 v19, v1
	v_mov_b32_e32 v21, v1
	v_mov_b32_e32 v23, v1
	v_mov_b32_e32 v25, v1
	v_mov_b32_e32 v27, v1
	v_lshlrev_b32_e32 v0, 2, v11
	v_mov_b32_e32 v29, v1
	v_lshl_add_u64 v[30:31], s[14:15], 0, v[6:7]
	v_cndmask_b32_e64 v11, 0, 1, s[8:9]
	v_mov_b32_e32 v13, v9
	s_mov_b64 s[16:17], 0
	v_lshl_add_u64 v[14:15], v[30:31], 0, v[14:15]
	v_lshl_add_u64 v[16:17], v[30:31], 0, v[16:17]
	v_lshl_add_u64 v[18:19], v[30:31], 0, v[18:19]
	v_lshl_add_u64 v[20:21], v[30:31], 0, v[20:21]
	v_lshl_add_u64 v[22:23], v[30:31], 0, v[22:23]
	v_lshl_add_u64 v[24:25], v[30:31], 0, v[24:25]
	v_lshl_add_u64 v[26:27], v[30:31], 0, v[26:27]
	v_lshl_add_u64 v[28:29], v[30:31], 0, v[28:29]
	v_cmp_ne_u32_e64 s[8:9], 1, v11
	v_mov_b32_e32 v11, v38
	s_and_b64 vcc, exec, s[8:9]
	s_cbranch_vccnz .LBB0_1431
	v_mov_b32_e32 v122, v28
	v_mov_b32_e32 v123, v29
	v_lshl_add_u64 v[124:125], s[12:13], 0, v[12:13]
	v_mov_b32_e32 v126, v38
	s_mov_b32 s58, 0x4000
	s_mov_b32 s59, 0
	global_load_dword v130, v[122:123], off nt
	v_lshl_add_u64 v[122:123], v[122:123], 0, s[58:59]
	global_load_dword v131, v[122:123], off nt
	v_lshl_add_u64 v[122:123], v[122:123], 0, s[58:59]
	global_load_dword v132, v[122:123], off nt
	v_lshl_add_u64 v[122:123], v[122:123], 0, s[58:59]
	global_load_dword v133, v[122:123], off nt
	v_lshl_add_u64 v[122:123], v[122:123], 0, s[58:59]
	global_load_dword v134, v[122:123], off nt
	v_lshl_add_u64 v[122:123], v[122:123], 0, s[58:59]
	global_load_dword v135, v[122:123], off nt
	v_lshl_add_u64 v[122:123], v[122:123], 0, s[58:59]
	global_load_dword v136, v[122:123], off nt
	v_lshl_add_u64 v[122:123], v[122:123], 0, s[58:59]
	global_load_dword v137, v[122:123], off nt
	v_lshl_add_u64 v[122:123], v[122:123], 0, s[58:59]
	global_load_dword v138, v[122:123], off nt
	v_lshl_add_u64 v[122:123], v[122:123], 0, s[58:59]
	global_load_dword v139, v[122:123], off nt
	v_lshl_add_u64 v[122:123], v[122:123], 0, s[58:59]
	global_load_dword v140, v[122:123], off nt
	v_lshl_add_u64 v[122:123], v[122:123], 0, s[58:59]
	global_load_dword v141, v[122:123], off nt
	v_lshl_add_u64 v[122:123], v[122:123], 0, s[58:59]
	global_load_dword v142, v[122:123], off nt
	v_lshl_add_u64 v[122:123], v[122:123], 0, s[58:59]
	global_load_dword v143, v[122:123], off nt
	v_lshl_add_u64 v[122:123], v[122:123], 0, s[58:59]
	global_load_dword v144, v[122:123], off nt
	v_lshl_add_u64 v[122:123], v[122:123], 0, s[58:59]
	global_load_dword v145, v[122:123], off nt
	v_lshl_add_u64 v[122:123], v[122:123], 0, s[58:59]
	global_load_dword v146, v[122:123], off nt
	v_lshl_add_u64 v[122:123], v[122:123], 0, s[58:59]
	global_load_dword v147, v[122:123], off nt
	v_lshl_add_u64 v[122:123], v[122:123], 0, s[58:59]
	global_load_dword v148, v[122:123], off nt
	v_lshl_add_u64 v[122:123], v[122:123], 0, s[58:59]
	global_load_dword v149, v[122:123], off nt
	v_lshl_add_u64 v[122:123], v[122:123], 0, s[58:59]
	global_load_dword v150, v[122:123], off nt
	v_lshl_add_u64 v[122:123], v[122:123], 0, s[58:59]
	global_load_dword v151, v[122:123], off nt
	v_lshl_add_u64 v[122:123], v[122:123], 0, s[58:59]
	global_load_dword v152, v[122:123], off nt
	v_lshl_add_u64 v[122:123], v[122:123], 0, s[58:59]
	global_load_dword v153, v[122:123], off nt
	v_lshl_add_u64 v[122:123], v[122:123], 0, s[58:59]
	global_load_dword v154, v[122:123], off nt
	v_lshl_add_u64 v[122:123], v[122:123], 0, s[58:59]
	global_load_dword v155, v[122:123], off nt
	v_lshl_add_u64 v[122:123], v[122:123], 0, s[58:59]
	global_load_dword v156, v[122:123], off nt
	v_lshl_add_u64 v[122:123], v[122:123], 0, s[58:59]
	global_load_dword v157, v[122:123], off nt
	v_lshl_add_u64 v[122:123], v[122:123], 0, s[58:59]
	global_load_dword v158, v[122:123], off nt
	v_lshl_add_u64 v[122:123], v[122:123], 0, s[58:59]
	global_load_dword v159, v[122:123], off nt
	v_lshl_add_u64 v[122:123], v[122:123], 0, s[58:59]
	global_load_dword v160, v[122:123], off nt
	v_lshl_add_u64 v[122:123], v[122:123], 0, s[58:59]
	global_load_dword v161, v[122:123], off nt
	global_load_dword v162, v[124:125], off
	global_load_dword v163, v[124:125], off offset:8
	global_load_dword v164, v[124:125], off offset:16
	global_load_dword v165, v[124:125], off offset:24
	global_load_dword v166, v[124:125], off offset:32
	global_load_dword v167, v[124:125], off offset:40
	global_load_dword v168, v[124:125], off offset:48
	global_load_dword v169, v[124:125], off offset:56
	global_load_dword v170, v[124:125], off offset:64
	global_load_dword v171, v[124:125], off offset:72
	global_load_dword v172, v[124:125], off offset:80
	global_load_dword v173, v[124:125], off offset:88
	global_load_dword v174, v[124:125], off offset:96
	global_load_dword v175, v[124:125], off offset:104
	global_load_dword v176, v[124:125], off offset:112
	global_load_dword v177, v[124:125], off offset:120
	s_waitcnt vmcnt(15)
	v_mul_f32_e32 v130, v130, v162
	ds_write_b32 v126, v130
	s_waitcnt vmcnt(14)
	v_mul_f32_e32 v131, v131, v163
	ds_write_b32 v126, v131 offset:264
	s_waitcnt vmcnt(13)
	v_mul_f32_e32 v132, v132, v164
	ds_write_b32 v126, v132 offset:528
	s_waitcnt vmcnt(12)
	v_mul_f32_e32 v133, v133, v165
	ds_write_b32 v126, v133 offset:792
	s_waitcnt vmcnt(11)
	v_mul_f32_e32 v134, v134, v166
	ds_write_b32 v126, v134 offset:1056
	s_waitcnt vmcnt(10)
	v_mul_f32_e32 v135, v135, v167
	ds_write_b32 v126, v135 offset:1320
	s_waitcnt vmcnt(9)
	v_mul_f32_e32 v136, v136, v168
	ds_write_b32 v126, v136 offset:1584
	s_waitcnt vmcnt(8)
	v_mul_f32_e32 v137, v137, v169
	ds_write_b32 v126, v137 offset:1848
	s_waitcnt vmcnt(7)
	v_mul_f32_e32 v138, v138, v170
	ds_write_b32 v126, v138 offset:2112
	s_waitcnt vmcnt(6)
	v_mul_f32_e32 v139, v139, v171
	ds_write_b32 v126, v139 offset:2376
	s_waitcnt vmcnt(5)
	v_mul_f32_e32 v140, v140, v172
	ds_write_b32 v126, v140 offset:2640
	s_waitcnt vmcnt(4)
	v_mul_f32_e32 v141, v141, v173
	ds_write_b32 v126, v141 offset:2904
	s_waitcnt vmcnt(3)
	v_mul_f32_e32 v142, v142, v174
	ds_write_b32 v126, v142 offset:3168
	s_waitcnt vmcnt(2)
	v_mul_f32_e32 v143, v143, v175
	ds_write_b32 v126, v143 offset:3432
	s_waitcnt vmcnt(1)
	v_mul_f32_e32 v144, v144, v176
	ds_write_b32 v126, v144 offset:3696
	s_waitcnt vmcnt(0)
	v_mul_f32_e32 v145, v145, v177
	ds_write_b32 v126, v145 offset:3960
	global_load_dword v162, v[124:125], off offset:128
	global_load_dword v163, v[124:125], off offset:136
	global_load_dword v164, v[124:125], off offset:144
	global_load_dword v165, v[124:125], off offset:152
	global_load_dword v166, v[124:125], off offset:160
	global_load_dword v167, v[124:125], off offset:168
	global_load_dword v168, v[124:125], off offset:176
	global_load_dword v169, v[124:125], off offset:184
	global_load_dword v170, v[124:125], off offset:192
	global_load_dword v171, v[124:125], off offset:200
	global_load_dword v172, v[124:125], off offset:208
	global_load_dword v173, v[124:125], off offset:216
	global_load_dword v174, v[124:125], off offset:224
	global_load_dword v175, v[124:125], off offset:232
	global_load_dword v176, v[124:125], off offset:240
	global_load_dword v177, v[124:125], off offset:248
	s_waitcnt vmcnt(15)
	v_mul_f32_e32 v146, v146, v162
	ds_write_b32 v126, v146 offset:4224
	s_waitcnt vmcnt(14)
	v_mul_f32_e32 v147, v147, v163
	ds_write_b32 v126, v147 offset:4488
	s_waitcnt vmcnt(13)
	v_mul_f32_e32 v148, v148, v164
	ds_write_b32 v126, v148 offset:4752
	s_waitcnt vmcnt(12)
	v_mul_f32_e32 v149, v149, v165
	ds_write_b32 v126, v149 offset:5016
	s_waitcnt vmcnt(11)
	v_mul_f32_e32 v150, v150, v166
	ds_write_b32 v126, v150 offset:5280
	s_waitcnt vmcnt(10)
	v_mul_f32_e32 v151, v151, v167
	ds_write_b32 v126, v151 offset:5544
	s_waitcnt vmcnt(9)
	v_mul_f32_e32 v152, v152, v168
	ds_write_b32 v126, v152 offset:5808
	s_waitcnt vmcnt(8)
	v_mul_f32_e32 v153, v153, v169
	ds_write_b32 v126, v153 offset:6072
	s_waitcnt vmcnt(7)
	v_mul_f32_e32 v154, v154, v170
	ds_write_b32 v126, v154 offset:6336
	s_waitcnt vmcnt(6)
	v_mul_f32_e32 v155, v155, v171
	ds_write_b32 v126, v155 offset:6600
	s_waitcnt vmcnt(5)
	v_mul_f32_e32 v156, v156, v172
	ds_write_b32 v126, v156 offset:6864
	s_waitcnt vmcnt(4)
	v_mul_f32_e32 v157, v157, v173
	ds_write_b32 v126, v157 offset:7128
	s_waitcnt vmcnt(3)
	v_mul_f32_e32 v158, v158, v174
	ds_write_b32 v126, v158 offset:7392
	s_waitcnt vmcnt(2)
	v_mul_f32_e32 v159, v159, v175
	ds_write_b32 v126, v159 offset:7656
	s_waitcnt vmcnt(1)
	v_mul_f32_e32 v160, v160, v176
	ds_write_b32 v126, v160 offset:7920
	s_waitcnt vmcnt(0)
	v_mul_f32_e32 v161, v161, v177
	ds_write_b32 v126, v161 offset:8184
	s_branch .LBB0_1447
